# first K-loop iteration peeled with zero C operands in the N1024, tail and dqkv GEMM loops as well (accumulator zeroing removed)
# baseline (speedup 1.0000x reference)
;     __device__ __forceinline__ bool next(int i, Unit& u) const { if (i > 0 || c >= nN) return false; u.pm = pm; u.pn = c; return true; }
; #define PG8_STAGE(bufoff, gbase, voff) do { _Pragma("unroll") for (int _i = 0; _i < 2; ++_i) \
;         __builtin_amdgcn_global_load_lds((const unsigned*)((const char*)(gbase) + (size_t)_i * r64##voff + voff), (PG8_LAS unsigned*)(lds + (bufoff) + ldsw + _i * 8192), 16, 0, 0); } while (0)
; #define PG8_LDA(dst, b, h) do { _Pragma("unroll") for (int m = 0; m < 4; ++m) _Pragma("unroll") for (int k = 0; k < 2; ++k) dst[m][k] = *(const PG8_LAS bf16x8*)(lds + PG8_SA(b, h) + aoff + m * 2048 + k * 1024); } while (0)
; #define PG8_LDB(dst, b, h) do { _Pragma("unroll") for (int n = 0; n < 2; ++n) _Pragma("unroll") for (int k = 0; k < 2; ++k) dst[n][k] = *(const PG8_LAS bf16x8*)(lds + PG8_SB(b, h) + boff + n * 2048 + k * 1024); } while (0)
; #define PG8_WAIT_V(n) asm volatile("s_waitcnt vmcnt(" #n ")" ::: "memory")
; #define PG8_WAIT_L(n) asm volatile("s_waitcnt lgkmcnt(" #n ")" ::: "memory")
; template <class Epi, class Sched, bool ALIGN_EPI = false, bool SP2 = false>
; __device__ __forceinline__ void gemm_phase(PG8_LAS unsigned char* lds, const Gemm g, const Sched& S, const Epi& E, int wid0) {
;     ...
;         const bool has_next = S.next(ui + 1, nxt);
;         const char* nA = has_next ? PG8_APTR(nxt) : cA; const char* nB = has_next ? (const char*)g.Bt + (size_t)nxt.pn * tstepB : cB;
;         for (int t = 0; t < nt; t += 2) {
;             const bool last = (t == nt - 2);
;             const char* a1 = cA + (size_t)(t + 1) * kstep;
;             const char* a2 = last ? nA : cA + (size_t)(t + 2) * kstep; const char* b2 = last ? nB : cB + (size_t)(t + 2) * kstep;
;             const char* a3 = a2 + kstep; const char* b3 = b2 + kstep;
;             if (last && has_next) S.a_ready(nxt);
;             if constexpr (SP2) {
;             PG8_LDB(B0, 0, 0); PG8_LDB(B1, 0, 1); PG8_SCHED; PG8_LDA(At, 0, 0); PG8_STAGE(PG8_SA(1, 1), a1 + hstepA, voffA);
;             PG8_WAIT_V(8); PG8_WAIT_L(0); PG8_BAR; PG8_MMA(0, 0, At, B0); PG8_MMA(0, 1, At, B1); PG8_BAR; PG8_SCHED;
;             PG8_LDA(At, 0, 1); PG8_STAGE(PG8_SB(0, 0), b2, voffB); PG8_STAGE(PG8_SB(0, 1), b2 + hstepB, voffB); PG8_STAGE(PG8_SA(0, 0), a2, voffA);
;             PG8_WAIT_V(8); PG8_WAIT_L(0); PG8_BAR; PG8_MMA(1, 0, At, B0); PG8_MMA(1, 1, At, B1); PG8_BAR; PG8_SCHED;
.LBB0_204:
	s_ashr_i32 s19, s18, 31
	s_lshl_b64 s[20:21], s[18:19], 19
	s_add_u32 s20, s34, s20
	s_addc_u32 s21, s35, s21
	s_and_b64 s[22:23], s[2:3], exec
	s_cselect_b32 s19, s21, s27
	s_cselect_b32 s25, s20, s26
	s_ashr_i32 s17, s16, 31
	s_lshl_b64 s[22:23], s[16:17], 19
	s_add_u32 s22, s36, s22
	s_addc_u32 s23, s37, s23
	s_and_b64 s[30:31], s[2:3], exec
	s_cselect_b32 s17, s23, s29
	s_cselect_b32 s30, s22, s28
	s_add_u32 s26, s26, 0x40080
	s_addc_u32 s27, s27, 0
	s_add_u32 s31, s28, 0x100
	s_addc_u32 s78, s29, 0
	s_mov_b32 s79, -2
	s_waitcnt vmcnt(0)
.Lpeel_dqkv:
	s_add_u32 s28, s26, 0xfffc0080
	s_addc_u32 s29, s27, -1
	s_add_i32 s86, 0, 0x10000
	s_cmp_eq_u32 s79, 12
	s_cselect_b32 s29, s19, s29
	s_cselect_b32 s28, s25, s28
	v_add_u32_e32 v144, s86, v1
	s_cselect_b32 s85, s17, s78
	s_cselect_b32 s84, s30, s31
	s_add_i32 s88, 0, 0x14000
	ds_read_b128 v[136:139], v144
	ds_read_b128 v[140:143], v144 offset:1024
	ds_read_b128 v[148:151], v144 offset:2048
	ds_read_b128 v[152:155], v144 offset:3072
	v_add_u32_e32 v144, s88, v1
	ds_read_b128 v[156:159], v144
	ds_read_b128 v[160:163], v144 offset:1024
	ds_read_b128 v[164:167], v144 offset:2048
	ds_read_b128 v[168:171], v144 offset:3072
	v_lshl_add_u64 v[144:145], s[26:27], 0, v[134:135]
	s_add_i32 m0, s5, 0xc000
	ds_read_b128 v[172:175], v146
	ds_read_b128 v[176:179], v146 offset:1024
	ds_read_b128 v[180:183], v146 offset:2048
	ds_read_b128 v[184:187], v146 offset:3072
	ds_read_b128 v[188:191], v146 offset:4096
	ds_read_b128 v[192:195], v146 offset:5120
	ds_read_b128 v[196:199], v146 offset:6144
	ds_read_b128 v[200:203], v146 offset:7168
	global_load_lds_dwordx4 v[144:145], off
	v_lshl_add_u64 v[144:145], v[144:145], 0, s[64:65]
	s_add_i32 m0, s5, 0xe000
	s_nop 0
	global_load_lds_dwordx4 v[144:145], off
	s_waitcnt vmcnt(8)
	s_waitcnt lgkmcnt(0)
	s_barrier
	s_setprio 1
	s_waitcnt lgkmcnt(0)
	v_mfma_f32_16x16x32_bf16 v[126:129], v[136:139], v[172:175], 0
	v_mfma_f32_16x16x32_bf16 v[122:125], v[148:151], v[172:175], 0
	v_mfma_f32_16x16x32_bf16 v[110:113], v[136:139], v[180:183], 0
	v_mfma_f32_16x16x32_bf16 v[106:109], v[148:151], v[180:183], 0
	v_mfma_f32_16x16x32_bf16 v[94:97], v[136:139], v[188:191], 0
	v_mfma_f32_16x16x32_bf16 v[90:93], v[148:151], v[188:191], 0
	v_mfma_f32_16x16x32_bf16 v[78:81], v[136:139], v[196:199], 0
	v_mfma_f32_16x16x32_bf16 v[74:77], v[148:151], v[196:199], 0
	v_mfma_f32_16x16x32_bf16 v[126:129], v[140:143], v[176:179], v[126:129]
	v_mfma_f32_16x16x32_bf16 v[122:125], v[152:155], v[176:179], v[122:125]
	v_mfma_f32_16x16x32_bf16 v[110:113], v[140:143], v[184:187], v[110:113]
	v_mfma_f32_16x16x32_bf16 v[106:109], v[152:155], v[184:187], v[106:109]
	v_mfma_f32_16x16x32_bf16 v[94:97], v[140:143], v[192:195], v[94:97]
	v_mfma_f32_16x16x32_bf16 v[90:93], v[152:155], v[192:195], v[90:93]
	v_mfma_f32_16x16x32_bf16 v[78:81], v[140:143], v[200:203], v[78:81]
	v_mfma_f32_16x16x32_bf16 v[74:77], v[152:155], v[200:203], v[74:77]
	s_setprio 0
	s_setprio 1
	v_mfma_f32_16x16x32_bf16 v[118:121], v[156:159], v[172:175], 0
	v_mfma_f32_16x16x32_bf16 v[114:117], v[164:167], v[172:175], 0
	v_mfma_f32_16x16x32_bf16 v[102:105], v[156:159], v[180:183], 0
	v_mfma_f32_16x16x32_bf16 v[98:101], v[164:167], v[180:183], 0
	v_mfma_f32_16x16x32_bf16 v[86:89], v[156:159], v[188:191], 0
	v_mfma_f32_16x16x32_bf16 v[82:85], v[164:167], v[188:191], 0
	v_mfma_f32_16x16x32_bf16 v[70:73], v[156:159], v[196:199], 0
	v_mfma_f32_16x16x32_bf16 v[66:69], v[164:167], v[196:199], 0
	v_mfma_f32_16x16x32_bf16 v[118:121], v[160:163], v[176:179], v[118:121]
	v_mfma_f32_16x16x32_bf16 v[114:117], v[168:171], v[176:179], v[114:117]
	v_mfma_f32_16x16x32_bf16 v[102:105], v[160:163], v[184:187], v[102:105]
	v_mfma_f32_16x16x32_bf16 v[98:101], v[168:171], v[184:187], v[98:101]
	v_mfma_f32_16x16x32_bf16 v[86:89], v[160:163], v[192:195], v[86:89]
	v_mfma_f32_16x16x32_bf16 v[82:85], v[168:171], v[192:195], v[82:85]
	v_mfma_f32_16x16x32_bf16 v[70:73], v[160:163], v[200:203], v[70:73]
	v_mfma_f32_16x16x32_bf16 v[66:69], v[168:171], v[200:203], v[66:69]
	s_setprio 0
	s_barrier
	v_lshl_add_u64 v[144:145], s[84:85], 0, v[132:133]
	s_add_i32 s84, s86, s40
	s_mov_b32 m0, s84
	ds_read_b128 v[172:175], v146 offset:16384
	ds_read_b128 v[176:179], v146 offset:17408
	ds_read_b128 v[180:183], v146 offset:18432
	ds_read_b128 v[184:187], v146 offset:19456
	ds_read_b128 v[188:191], v146 offset:20480
	ds_read_b128 v[192:195], v146 offset:21504
	ds_read_b128 v[196:199], v146 offset:22528
	ds_read_b128 v[200:203], v146 offset:23552
	global_load_lds_dwordx4 v[144:145], off
	v_lshl_add_u64 v[204:205], v[144:145], 0, s[64:65]
	s_add_i32 m0, s84, 0x2000
	s_add_i32 s84, s88, s40
	global_load_lds_dwordx4 v[204:205], off
	v_lshl_add_u64 v[204:205], v[144:145], 0, s[66:67]
	s_mov_b32 m0, s84
	s_nop 0
	global_load_lds_dwordx4 v[204:205], off
	v_lshl_add_u64 v[204:205], v[144:145], 0, s[68:69]
	s_add_i32 m0, s84, 0x2000
	s_nop 0
	global_load_lds_dwordx4 v[204:205], off
	v_lshl_add_u64 v[204:205], s[28:29], 0, v[130:131]
	s_mov_b32 m0, s5
	v_lshl_add_u64 v[206:207], v[204:205], 0, s[64:65]
	global_load_lds_dwordx4 v[204:205], off
	s_mov_b32 m0, s41
	s_nop 0
	global_load_lds_dwordx4 v[206:207], off
	s_waitcnt vmcnt(8)
	s_waitcnt lgkmcnt(0)
	s_barrier
; #define PG8_STAGE(bufoff, gbase, voff) do { _Pragma("unroll") for (int _i = 0; _i < 2; ++_i) \
;         __builtin_amdgcn_global_load_lds((const unsigned*)((const char*)(gbase) + (size_t)_i * r64##voff + voff), (PG8_LAS unsigned*)(lds + (bufoff) + ldsw + _i * 8192), 16, 0, 0); } while (0)
; #define PG8_LDA(dst, b, h) do { _Pragma("unroll") for (int m = 0; m < 4; ++m) _Pragma("unroll") for (int k = 0; k < 2; ++k) dst[m][k] = *(const PG8_LAS bf16x8*)(lds + PG8_SA(b, h) + aoff + m * 2048 + k * 1024); } while (0)
; #define PG8_LDB(dst, b, h) do { _Pragma("unroll") for (int n = 0; n < 2; ++n) _Pragma("unroll") for (int k = 0; k < 2; ++k) dst[n][k] = *(const PG8_LAS bf16x8*)(lds + PG8_SB(b, h) + boff + n * 2048 + k * 1024); } while (0)
; #define PG8_MMA(ai, bj, At, Bt) do { __builtin_amdgcn_s_setprio(1); _Pragma("unroll") for (int m = 0; m < 4; ++m) _Pragma("unroll") for (int n = 0; n < 2; ++n) _Pragma("unroll") for (int k = 0; k < 2; ++k) \
;         acc[ai][bj][m][n] = __builtin_amdgcn_mfma_f32_16x16x32_bf16(Bt[n][k], At[m][k], acc[ai][bj][m][n], 0, 0, 0); __builtin_amdgcn_s_setprio(0); } while (0)
; #define PG8_WAIT_V(n) asm volatile("s_waitcnt vmcnt(" #n ")" ::: "memory")
; #define PG8_WAIT_L(n) asm volatile("s_waitcnt lgkmcnt(" #n ")" ::: "memory")
; #define PG8_BAR __builtin_amdgcn_s_barrier()
; #define PG8_SCHED __builtin_amdgcn_sched_barrier(0)
; template <class Epi, class Sched, bool ALIGN_EPI = false, bool SP2 = false>
; __device__ __forceinline__ void gemm_phase(PG8_LAS unsigned char* lds, const Gemm g, const Sched& S, const Epi& E, int wid0) {
;     ...
;             PG8_WAIT_V(8); PG8_WAIT_L(0); PG8_BAR; PG8_MMA(1, 0, At, B0); PG8_MMA(1, 1, At, B1); PG8_BAR; PG8_SCHED;
;             PG8_LDB(B0, 1, 0); PG8_LDB(B1, 1, 1); PG8_SCHED; PG8_LDA(At, 1, 0); PG8_STAGE(PG8_SA(0, 1), a2 + hstepA, voffA);
;             PG8_WAIT_V(8); PG8_WAIT_L(0); PG8_BAR; PG8_MMA(0, 0, At, B0); PG8_MMA(0, 1, At, B1); PG8_BAR; PG8_SCHED;
	s_setprio 1
	s_waitcnt lgkmcnt(0)
	v_mfma_f32_16x16x32_bf16 v[62:65], v[136:139], v[172:175], 0
	v_mfma_f32_16x16x32_bf16 v[58:61], v[148:151], v[172:175], 0
	v_mfma_f32_16x16x32_bf16 v[46:49], v[136:139], v[180:183], 0
	v_mfma_f32_16x16x32_bf16 v[42:45], v[148:151], v[180:183], 0
	v_mfma_f32_16x16x32_bf16 v[30:33], v[136:139], v[188:191], 0
	v_mfma_f32_16x16x32_bf16 v[26:29], v[148:151], v[188:191], 0
	v_mfma_f32_16x16x32_bf16 v[14:17], v[136:139], v[196:199], 0
	v_mfma_f32_16x16x32_bf16 v[10:13], v[148:151], v[196:199], 0
	v_mfma_f32_16x16x32_bf16 v[62:65], v[140:143], v[176:179], v[62:65]
	v_mfma_f32_16x16x32_bf16 v[58:61], v[152:155], v[176:179], v[58:61]
	v_mfma_f32_16x16x32_bf16 v[46:49], v[140:143], v[184:187], v[46:49]
	v_mfma_f32_16x16x32_bf16 v[42:45], v[152:155], v[184:187], v[42:45]
	v_mfma_f32_16x16x32_bf16 v[30:33], v[140:143], v[192:195], v[30:33]
	v_mfma_f32_16x16x32_bf16 v[26:29], v[152:155], v[192:195], v[26:29]
	v_mfma_f32_16x16x32_bf16 v[14:17], v[140:143], v[200:203], v[14:17]
	v_mfma_f32_16x16x32_bf16 v[10:13], v[152:155], v[200:203], v[10:13]
	s_setprio 0
	s_setprio 1
	v_mfma_f32_16x16x32_bf16 v[54:57], v[156:159], v[172:175], 0
	v_mfma_f32_16x16x32_bf16 v[50:53], v[164:167], v[172:175], 0
	v_mfma_f32_16x16x32_bf16 v[38:41], v[156:159], v[180:183], 0
	v_mfma_f32_16x16x32_bf16 v[34:37], v[164:167], v[180:183], 0
	v_mfma_f32_16x16x32_bf16 v[22:25], v[156:159], v[188:191], 0
	v_mfma_f32_16x16x32_bf16 v[18:21], v[164:167], v[188:191], 0
	v_mfma_f32_16x16x32_bf16 v[6:9], v[156:159], v[196:199], 0
	v_mfma_f32_16x16x32_bf16 v[2:5], v[164:167], v[196:199], 0
	v_mfma_f32_16x16x32_bf16 v[54:57], v[160:163], v[176:179], v[54:57]
	v_mfma_f32_16x16x32_bf16 v[50:53], v[168:171], v[176:179], v[50:53]
	v_mfma_f32_16x16x32_bf16 v[38:41], v[160:163], v[184:187], v[38:41]
	v_mfma_f32_16x16x32_bf16 v[34:37], v[168:171], v[184:187], v[34:37]
	v_mfma_f32_16x16x32_bf16 v[22:25], v[160:163], v[192:195], v[22:25]
	v_mfma_f32_16x16x32_bf16 v[18:21], v[168:171], v[192:195], v[18:21]
	v_mfma_f32_16x16x32_bf16 v[6:9], v[160:163], v[200:203], v[6:9]
	v_mfma_f32_16x16x32_bf16 v[2:5], v[168:171], v[200:203], v[2:5]
	s_setprio 0
	s_barrier
	s_add_i32 s28, 0, 0x18000
	v_add_u32_e32 v147, s28, v1
	s_add_i32 s29, 0, 0x1c000
	ds_read_b128 v[136:139], v147
	ds_read_b128 v[140:143], v147 offset:1024
	ds_read_b128 v[148:151], v147 offset:2048
	ds_read_b128 v[152:155], v147 offset:3072
	v_add_u32_e32 v147, s29, v1
	ds_read_b128 v[156:159], v147
	ds_read_b128 v[160:163], v147 offset:1024
	ds_read_b128 v[164:167], v147 offset:2048
	ds_read_b128 v[168:171], v147 offset:3072
	s_mov_b32 m0, s43
	v_lshl_add_u64 v[206:207], v[204:205], 0, s[66:67]
	ds_read_b128 v[172:175], v146 offset:32768
	ds_read_b128 v[176:179], v146 offset:33792
	ds_read_b128 v[180:183], v146 offset:34816
	ds_read_b128 v[184:187], v146 offset:35840
	ds_read_b128 v[188:191], v146 offset:36864
	ds_read_b128 v[192:195], v146 offset:37888
	ds_read_b128 v[196:199], v146 offset:38912
	ds_read_b128 v[200:203], v146 offset:39936
	global_load_lds_dwordx4 v[206:207], off
	v_lshl_add_u64 v[206:207], v[204:205], 0, s[68:69]
	s_mov_b32 m0, s44
	s_nop 0
	global_load_lds_dwordx4 v[206:207], off
	s_waitcnt vmcnt(8)
	s_waitcnt lgkmcnt(0)
	s_barrier
	s_setprio 1
	s_waitcnt lgkmcnt(0)
	v_mfma_f32_16x16x32_bf16 v[126:129], v[136:139], v[172:175], v[126:129]
	v_mfma_f32_16x16x32_bf16 v[122:125], v[148:151], v[172:175], v[122:125]
	v_mfma_f32_16x16x32_bf16 v[110:113], v[136:139], v[180:183], v[110:113]
	v_mfma_f32_16x16x32_bf16 v[106:109], v[148:151], v[180:183], v[106:109]
	v_mfma_f32_16x16x32_bf16 v[94:97], v[136:139], v[188:191], v[94:97]
	v_mfma_f32_16x16x32_bf16 v[90:93], v[148:151], v[188:191], v[90:93]
	v_mfma_f32_16x16x32_bf16 v[78:81], v[136:139], v[196:199], v[78:81]
	v_mfma_f32_16x16x32_bf16 v[74:77], v[148:151], v[196:199], v[74:77]
	v_mfma_f32_16x16x32_bf16 v[126:129], v[140:143], v[176:179], v[126:129]
	v_mfma_f32_16x16x32_bf16 v[122:125], v[152:155], v[176:179], v[122:125]
	v_mfma_f32_16x16x32_bf16 v[110:113], v[140:143], v[184:187], v[110:113]
	v_mfma_f32_16x16x32_bf16 v[106:109], v[152:155], v[184:187], v[106:109]
	v_mfma_f32_16x16x32_bf16 v[94:97], v[140:143], v[192:195], v[94:97]
	v_mfma_f32_16x16x32_bf16 v[90:93], v[152:155], v[192:195], v[90:93]
	v_mfma_f32_16x16x32_bf16 v[78:81], v[140:143], v[200:203], v[78:81]
	v_mfma_f32_16x16x32_bf16 v[74:77], v[152:155], v[200:203], v[74:77]
	s_setprio 0
	s_setprio 1
	v_mfma_f32_16x16x32_bf16 v[118:121], v[156:159], v[172:175], v[118:121]
	v_mfma_f32_16x16x32_bf16 v[114:117], v[164:167], v[172:175], v[114:117]
	v_mfma_f32_16x16x32_bf16 v[102:105], v[156:159], v[180:183], v[102:105]
	v_mfma_f32_16x16x32_bf16 v[98:101], v[164:167], v[180:183], v[98:101]
	v_mfma_f32_16x16x32_bf16 v[86:89], v[156:159], v[188:191], v[86:89]
	v_mfma_f32_16x16x32_bf16 v[82:85], v[164:167], v[188:191], v[82:85]
	v_mfma_f32_16x16x32_bf16 v[70:73], v[156:159], v[196:199], v[70:73]
	v_mfma_f32_16x16x32_bf16 v[66:69], v[164:167], v[196:199], v[66:69]
	v_mfma_f32_16x16x32_bf16 v[118:121], v[160:163], v[176:179], v[118:121]
	v_mfma_f32_16x16x32_bf16 v[114:117], v[168:171], v[176:179], v[114:117]
	v_mfma_f32_16x16x32_bf16 v[102:105], v[160:163], v[184:187], v[102:105]
	v_mfma_f32_16x16x32_bf16 v[98:101], v[168:171], v[184:187], v[98:101]
	v_mfma_f32_16x16x32_bf16 v[86:89], v[160:163], v[192:195], v[86:89]
	v_mfma_f32_16x16x32_bf16 v[82:85], v[168:171], v[192:195], v[82:85]
	v_mfma_f32_16x16x32_bf16 v[70:73], v[160:163], v[200:203], v[70:73]
	v_mfma_f32_16x16x32_bf16 v[66:69], v[168:171], v[200:203], v[66:69]
	s_setprio 0
	s_barrier
; #define PG8_STAGE(bufoff, gbase, voff) do { _Pragma("unroll") for (int _i = 0; _i < 2; ++_i) \
;         __builtin_amdgcn_global_load_lds((const unsigned*)((const char*)(gbase) + (size_t)_i * r64##voff + voff), (PG8_LAS unsigned*)(lds + (bufoff) + ldsw + _i * 8192), 16, 0, 0); } while (0)
; #define PG8_LDA(dst, b, h) do { _Pragma("unroll") for (int m = 0; m < 4; ++m) _Pragma("unroll") for (int k = 0; k < 2; ++k) dst[m][k] = *(const PG8_LAS bf16x8*)(lds + PG8_SA(b, h) + aoff + m * 2048 + k * 1024); } while (0)
; #define PG8_MMA(ai, bj, At, Bt) do { __builtin_amdgcn_s_setprio(1); _Pragma("unroll") for (int m = 0; m < 4; ++m) _Pragma("unroll") for (int n = 0; n < 2; ++n) _Pragma("unroll") for (int k = 0; k < 2; ++k) \
;         acc[ai][bj][m][n] = __builtin_amdgcn_mfma_f32_16x16x32_bf16(Bt[n][k], At[m][k], acc[ai][bj][m][n], 0, 0, 0); __builtin_amdgcn_s_setprio(0); } while (0)
; #define PG8_WAIT_V(n) asm volatile("s_waitcnt vmcnt(" #n ")" ::: "memory")
; #define PG8_WAIT_L(n) asm volatile("s_waitcnt lgkmcnt(" #n ")" ::: "memory")
; #define PG8_BAR __builtin_amdgcn_s_barrier()
; #define PG8_SCHED __builtin_amdgcn_sched_barrier(0)
; template <class Epi, class Sched, bool ALIGN_EPI = false, bool SP2 = false>
; __device__ __forceinline__ void gemm_phase(PG8_LAS unsigned char* lds, const Gemm g, const Sched& S, const Epi& E, int wid0) {
;     ...
;             PG8_LDA(At, 1, 1); PG8_STAGE(PG8_SB(1, 0), b3, voffB); PG8_STAGE(PG8_SB(1, 1), b3 + hstepB, voffB); PG8_STAGE(PG8_SA(1, 0), a3, voffA);
;             PG8_WAIT_V(8); PG8_WAIT_L(0); PG8_BAR; PG8_MMA(1, 0, At, B0); PG8_MMA(1, 1, At, B1); PG8_BAR; PG8_SCHED;
	s_add_i32 s28, s28, s40
	v_lshl_add_u64 v[206:207], v[144:145], 0, s[70:71]
	s_mov_b32 m0, s28
	ds_read_b128 v[172:175], v146 offset:49152
	ds_read_b128 v[176:179], v146 offset:50176
	ds_read_b128 v[180:183], v146 offset:51200
	ds_read_b128 v[184:187], v146 offset:52224
	ds_read_b128 v[188:191], v146 offset:53248
	ds_read_b128 v[192:195], v146 offset:54272
	ds_read_b128 v[196:199], v146 offset:55296
	ds_read_b128 v[200:203], v146 offset:56320
	global_load_lds_dwordx4 v[206:207], off
	v_lshl_add_u64 v[206:207], v[144:145], 0, s[72:73]
	s_add_i32 m0, s28, 0x2000
	s_add_i32 s28, s29, s40
	global_load_lds_dwordx4 v[206:207], off
	v_lshl_add_u64 v[206:207], v[144:145], 0, s[74:75]
	s_mov_b32 m0, s28
	v_lshl_add_u64 v[144:145], v[144:145], 0, s[76:77]
	global_load_lds_dwordx4 v[206:207], off
	s_add_i32 m0, s28, 0x2000
	s_nop 0
	global_load_lds_dwordx4 v[144:145], off
	v_lshl_add_u64 v[144:145], v[204:205], 0, s[70:71]
	s_mov_b32 m0, s45
	s_nop 0
	global_load_lds_dwordx4 v[144:145], off
	v_lshl_add_u64 v[144:145], v[204:205], 0, s[72:73]
	s_mov_b32 m0, s46
	s_nop 0
	global_load_lds_dwordx4 v[144:145], off
	s_waitcnt vmcnt(8)
	s_waitcnt lgkmcnt(0)
	s_barrier
	s_setprio 1
	s_waitcnt lgkmcnt(0)
	v_mfma_f32_16x16x32_bf16 v[62:65], v[136:139], v[172:175], v[62:65]
	v_mfma_f32_16x16x32_bf16 v[58:61], v[148:151], v[172:175], v[58:61]
	v_mfma_f32_16x16x32_bf16 v[46:49], v[136:139], v[180:183], v[46:49]
	v_mfma_f32_16x16x32_bf16 v[42:45], v[148:151], v[180:183], v[42:45]
	v_mfma_f32_16x16x32_bf16 v[30:33], v[136:139], v[188:191], v[30:33]
	v_mfma_f32_16x16x32_bf16 v[26:29], v[148:151], v[188:191], v[26:29]
	v_mfma_f32_16x16x32_bf16 v[14:17], v[136:139], v[196:199], v[14:17]
	v_mfma_f32_16x16x32_bf16 v[10:13], v[148:151], v[196:199], v[10:13]
	v_mfma_f32_16x16x32_bf16 v[62:65], v[140:143], v[176:179], v[62:65]
	v_mfma_f32_16x16x32_bf16 v[58:61], v[152:155], v[176:179], v[58:61]
	v_mfma_f32_16x16x32_bf16 v[46:49], v[140:143], v[184:187], v[46:49]
	v_mfma_f32_16x16x32_bf16 v[42:45], v[152:155], v[184:187], v[42:45]
	v_mfma_f32_16x16x32_bf16 v[30:33], v[140:143], v[192:195], v[30:33]
	v_mfma_f32_16x16x32_bf16 v[26:29], v[152:155], v[192:195], v[26:29]
	v_mfma_f32_16x16x32_bf16 v[14:17], v[140:143], v[200:203], v[14:17]
	v_mfma_f32_16x16x32_bf16 v[10:13], v[152:155], v[200:203], v[10:13]
	s_setprio 0
	s_setprio 1
	v_mfma_f32_16x16x32_bf16 v[54:57], v[156:159], v[172:175], v[54:57]
	v_mfma_f32_16x16x32_bf16 v[50:53], v[164:167], v[172:175], v[50:53]
	v_mfma_f32_16x16x32_bf16 v[38:41], v[156:159], v[180:183], v[38:41]
	v_mfma_f32_16x16x32_bf16 v[34:37], v[164:167], v[180:183], v[34:37]
	v_mfma_f32_16x16x32_bf16 v[22:25], v[156:159], v[188:191], v[22:25]
	v_mfma_f32_16x16x32_bf16 v[18:21], v[164:167], v[188:191], v[18:21]
	v_mfma_f32_16x16x32_bf16 v[6:9], v[156:159], v[196:199], v[6:9]
	v_mfma_f32_16x16x32_bf16 v[2:5], v[164:167], v[196:199], v[2:5]
	v_mfma_f32_16x16x32_bf16 v[54:57], v[160:163], v[176:179], v[54:57]
	v_mfma_f32_16x16x32_bf16 v[50:53], v[168:171], v[176:179], v[50:53]
	v_mfma_f32_16x16x32_bf16 v[38:41], v[160:163], v[184:187], v[38:41]
	v_mfma_f32_16x16x32_bf16 v[34:37], v[168:171], v[184:187], v[34:37]
	v_mfma_f32_16x16x32_bf16 v[22:25], v[160:163], v[192:195], v[22:25]
	v_mfma_f32_16x16x32_bf16 v[18:21], v[168:171], v[192:195], v[18:21]
	v_mfma_f32_16x16x32_bf16 v[6:9], v[160:163], v[200:203], v[6:9]
	v_mfma_f32_16x16x32_bf16 v[2:5], v[168:171], v[200:203], v[2:5]
	s_setprio 0
	s_barrier
	s_add_i32 s79, s79, 2
	s_add_u32 s26, s26, 0x100
	s_addc_u32 s27, s27, 0
	s_add_u32 s31, s31, 0x100
	s_addc_u32 s78, s78, 0
	s_cmp_gt_u32 s79, 13
	s_cbranch_scc1 .Lpeel_x_dqkv

; #define PG8_BAR __builtin_amdgcn_s_barrier()
; template <class Epi, class Sched, bool ALIGN_EPI = false, bool SP2 = false>
; __device__ __forceinline__ void gemm_phase(PG8_LAS unsigned char* lds, const Gemm g, const Sched& S, const Epi& E, int wid0) {
;     ...
;         if constexpr (ALIGN_EPI) { if (wr == 0) PG8_BAR; }
.Lpeel_x_dqkv:
	s_and_b64 vcc, exec, s[14:15]
	s_cbranch_vccz .LBB0_208
	s_barrier

; #define PG8_STAGE(bufoff, gbase, voff) do { _Pragma("unroll") for (int _i = 0; _i < 2; ++_i) \
;         __builtin_amdgcn_global_load_lds((const unsigned*)((const char*)(gbase) + (size_t)_i * r64##voff + voff), (PG8_LAS unsigned*)(lds + (bufoff) + ldsw + _i * 8192), 16, 0, 0); } while (0)
; #define PG8_LDA(dst, b, h) do { _Pragma("unroll") for (int m = 0; m < 4; ++m) _Pragma("unroll") for (int k = 0; k < 2; ++k) dst[m][k] = *(const PG8_LAS bf16x8*)(lds + PG8_SA(b, h) + aoff + m * 2048 + k * 1024); } while (0)
; #define PG8_LDB(dst, b, h) do { _Pragma("unroll") for (int n = 0; n < 2; ++n) _Pragma("unroll") for (int k = 0; k < 2; ++k) dst[n][k] = *(const PG8_LAS bf16x8*)(lds + PG8_SB(b, h) + boff + n * 2048 + k * 1024); } while (0)
; #define PG8_MMA(ai, bj, At, Bt) do { __builtin_amdgcn_s_setprio(1); _Pragma("unroll") for (int m = 0; m < 4; ++m) _Pragma("unroll") for (int n = 0; n < 2; ++n) _Pragma("unroll") for (int k = 0; k < 2; ++k) \
;         acc[ai][bj][m][n] = __builtin_amdgcn_mfma_f32_16x16x32_bf16(Bt[n][k], At[m][k], acc[ai][bj][m][n], 0, 0, 0); __builtin_amdgcn_s_setprio(0); } while (0)
; #define PG8_WAIT_V(n) asm volatile("s_waitcnt vmcnt(" #n ")" ::: "memory")
; #define PG8_WAIT_L(n) asm volatile("s_waitcnt lgkmcnt(" #n ")" ::: "memory")
; template <class Epi, class Sched, bool ALIGN_EPI = false, bool SP2 = false>
; __device__ __forceinline__ void gemm_phase(PG8_LAS unsigned char* lds, const Gemm g, const Sched& S, const Epi& E, int wid0) {
;     ...
;             const bool last = (t == nt - 2);
;             const char* a1 = cA + (size_t)(t + 1) * kstep;
;             const char* a2 = last ? nA : cA + (size_t)(t + 2) * kstep; const char* b2 = last ? nB : cB + (size_t)(t + 2) * kstep;
;             const char* a3 = a2 + kstep; const char* b3 = b2 + kstep;
;             if (last && has_next) S.a_ready(nxt);
;             if constexpr (SP2) {
;             PG8_LDB(B0, 0, 0); PG8_LDB(B1, 0, 1); PG8_SCHED; PG8_LDA(At, 0, 0); PG8_STAGE(PG8_SA(1, 1), a1 + hstepA, voffA);
;             PG8_WAIT_V(8); PG8_WAIT_L(0); PG8_BAR; PG8_MMA(0, 0, At, B0); PG8_MMA(0, 1, At, B1); PG8_BAR; PG8_SCHED;
;             PG8_LDA(At, 0, 1); PG8_STAGE(PG8_SB(0, 0), b2, voffB); PG8_STAGE(PG8_SB(0, 1), b2 + hstepB, voffB); PG8_STAGE(PG8_SA(0, 0), a2, voffA);
;             PG8_WAIT_V(8); PG8_WAIT_L(0); PG8_BAR; PG8_MMA(1, 0, At, B0); PG8_MMA(1, 1, At, B1); PG8_BAR; PG8_SCHED;
.LBB0_697:
	s_add_u32 s4, s14, 0x80
	s_addc_u32 s5, s15, 0
	s_add_u32 s90, s92, 0x100
	s_addc_u32 s91, s93, 0
	s_mov_b32 s14, 0
	s_waitcnt vmcnt(0)
.Lpeel_n1024:
	s_add_i32 s92, s14, 2
	s_add_u32 s22, s4, 0x80
	s_addc_u32 s15, s5, 0
	s_add_i32 s63, 0, 0x10000
	s_cmp_eq_u32 s84, s14
	s_cselect_b32 s15, s59, s15
	s_cselect_b32 s14, s58, s22
	v_add_u32_e32 v142, s63, v1
	s_cselect_b32 s95, s79, s91
	s_cselect_b32 s94, s78, s90
	s_add_i32 s22, 0, 0x14000
	ds_read_b128 v[138:141], v142
	ds_read_b128 v[144:147], v142 offset:1024
	ds_read_b128 v[148:151], v142 offset:2048
	ds_read_b128 v[152:155], v142 offset:3072
	v_add_u32_e32 v142, s22, v1
	ds_read_b128 v[156:159], v142
	ds_read_b128 v[160:163], v142 offset:1024
	ds_read_b128 v[164:167], v142 offset:2048
	ds_read_b128 v[168:171], v142 offset:3072
	v_lshl_add_u64 v[204:205], s[4:5], 0, v[134:135]
	s_add_i32 m0, s19, 0xc000
	ds_read_b128 v[172:175], v143
	ds_read_b128 v[176:179], v143 offset:1024
	ds_read_b128 v[180:183], v143 offset:2048
	ds_read_b128 v[184:187], v143 offset:3072
	ds_read_b128 v[188:191], v143 offset:4096
	ds_read_b128 v[192:195], v143 offset:5120
	ds_read_b128 v[196:199], v143 offset:6144
	ds_read_b128 v[200:203], v143 offset:7168
	global_load_lds_dwordx4 v[204:205], off
	v_lshl_add_u64 v[204:205], s[4:5], 0, v[136:137]
	s_add_i32 m0, s19, 0xe000
	s_nop 0
	global_load_lds_dwordx4 v[204:205], off
	s_waitcnt vmcnt(8)
	s_waitcnt lgkmcnt(0)
	s_barrier
	s_setprio 1
	s_waitcnt lgkmcnt(0)
	v_mfma_f32_16x16x32_bf16 v[126:129], v[138:141], v[172:175], 0
	v_mfma_f32_16x16x32_bf16 v[122:125], v[148:151], v[172:175], 0
	v_mfma_f32_16x16x32_bf16 v[110:113], v[138:141], v[180:183], 0
	v_mfma_f32_16x16x32_bf16 v[106:109], v[148:151], v[180:183], 0
	v_mfma_f32_16x16x32_bf16 v[94:97], v[138:141], v[188:191], 0
	v_mfma_f32_16x16x32_bf16 v[90:93], v[148:151], v[188:191], 0
	v_mfma_f32_16x16x32_bf16 v[78:81], v[138:141], v[196:199], 0
	v_mfma_f32_16x16x32_bf16 v[74:77], v[148:151], v[196:199], 0
	v_mfma_f32_16x16x32_bf16 v[126:129], v[144:147], v[176:179], v[126:129]
	v_mfma_f32_16x16x32_bf16 v[122:125], v[152:155], v[176:179], v[122:125]
	v_mfma_f32_16x16x32_bf16 v[110:113], v[144:147], v[184:187], v[110:113]
	v_mfma_f32_16x16x32_bf16 v[106:109], v[152:155], v[184:187], v[106:109]
	v_mfma_f32_16x16x32_bf16 v[94:97], v[144:147], v[192:195], v[94:97]
	v_mfma_f32_16x16x32_bf16 v[90:93], v[152:155], v[192:195], v[90:93]
	v_mfma_f32_16x16x32_bf16 v[78:81], v[144:147], v[200:203], v[78:81]
	v_mfma_f32_16x16x32_bf16 v[74:77], v[152:155], v[200:203], v[74:77]
	s_setprio 0
	s_setprio 1
	v_mfma_f32_16x16x32_bf16 v[118:121], v[156:159], v[172:175], 0
	v_mfma_f32_16x16x32_bf16 v[114:117], v[164:167], v[172:175], 0
	v_mfma_f32_16x16x32_bf16 v[102:105], v[156:159], v[180:183], 0
	v_mfma_f32_16x16x32_bf16 v[98:101], v[164:167], v[180:183], 0
	v_mfma_f32_16x16x32_bf16 v[86:89], v[156:159], v[188:191], 0
	v_mfma_f32_16x16x32_bf16 v[82:85], v[164:167], v[188:191], 0
	v_mfma_f32_16x16x32_bf16 v[70:73], v[156:159], v[196:199], 0
	v_mfma_f32_16x16x32_bf16 v[66:69], v[164:167], v[196:199], 0
	v_mfma_f32_16x16x32_bf16 v[118:121], v[160:163], v[176:179], v[118:121]
	v_mfma_f32_16x16x32_bf16 v[114:117], v[168:171], v[176:179], v[114:117]
	v_mfma_f32_16x16x32_bf16 v[102:105], v[160:163], v[184:187], v[102:105]
	v_mfma_f32_16x16x32_bf16 v[98:101], v[168:171], v[184:187], v[98:101]
	v_mfma_f32_16x16x32_bf16 v[86:89], v[160:163], v[192:195], v[86:89]
	v_mfma_f32_16x16x32_bf16 v[82:85], v[168:171], v[192:195], v[82:85]
	v_mfma_f32_16x16x32_bf16 v[70:73], v[160:163], v[200:203], v[70:73]
	v_mfma_f32_16x16x32_bf16 v[66:69], v[168:171], v[200:203], v[66:69]
	s_setprio 0
	s_barrier
	s_add_i32 s63, s63, s17
	v_lshl_add_u64 v[204:205], s[94:95], 0, v[130:131]
	s_mov_b32 m0, s63
	ds_read_b128 v[172:175], v143 offset:16384
	ds_read_b128 v[176:179], v143 offset:17408
	ds_read_b128 v[180:183], v143 offset:18432
	ds_read_b128 v[184:187], v143 offset:19456
	ds_read_b128 v[188:191], v143 offset:20480
	ds_read_b128 v[192:195], v143 offset:21504
	ds_read_b128 v[196:199], v143 offset:22528
	ds_read_b128 v[200:203], v143 offset:23552
	global_load_lds_dwordx4 v[204:205], off
	s_add_i32 m0, s63, 0x2000
	s_add_u32 s94, s94, s49
	v_lshl_add_u64 v[206:207], v[204:205], 0, s[82:83]
	s_addc_u32 s95, s95, 0
	s_add_i32 s22, s22, s17
	global_load_lds_dwordx4 v[206:207], off
	v_lshl_add_u64 v[208:209], s[94:95], 0, v[130:131]
	s_mov_b32 m0, s22
	v_lshl_add_u64 v[210:211], v[208:209], 0, s[82:83]
	global_load_lds_dwordx4 v[208:209], off
	s_add_i32 m0, s22, 0x2000
	v_lshl_add_u64 v[212:213], s[14:15], 0, v[132:133]
	global_load_lds_dwordx4 v[210:211], off
	s_mov_b32 m0, s19
	v_lshl_add_u64 v[214:215], v[212:213], 0, s[36:37]
	global_load_lds_dwordx4 v[212:213], off
	s_mov_b32 m0, s20
	s_nop 0
	global_load_lds_dwordx4 v[214:215], off
	s_waitcnt vmcnt(8)
	s_waitcnt lgkmcnt(0)
	s_barrier
; #define PG8_STAGE(bufoff, gbase, voff) do { _Pragma("unroll") for (int _i = 0; _i < 2; ++_i) \
;         __builtin_amdgcn_global_load_lds((const unsigned*)((const char*)(gbase) + (size_t)_i * r64##voff + voff), (PG8_LAS unsigned*)(lds + (bufoff) + ldsw + _i * 8192), 16, 0, 0); } while (0)
; #define PG8_LDA(dst, b, h) do { _Pragma("unroll") for (int m = 0; m < 4; ++m) _Pragma("unroll") for (int k = 0; k < 2; ++k) dst[m][k] = *(const PG8_LAS bf16x8*)(lds + PG8_SA(b, h) + aoff + m * 2048 + k * 1024); } while (0)
; #define PG8_LDB(dst, b, h) do { _Pragma("unroll") for (int n = 0; n < 2; ++n) _Pragma("unroll") for (int k = 0; k < 2; ++k) dst[n][k] = *(const PG8_LAS bf16x8*)(lds + PG8_SB(b, h) + boff + n * 2048 + k * 1024); } while (0)
; #define PG8_MMA(ai, bj, At, Bt) do { __builtin_amdgcn_s_setprio(1); _Pragma("unroll") for (int m = 0; m < 4; ++m) _Pragma("unroll") for (int n = 0; n < 2; ++n) _Pragma("unroll") for (int k = 0; k < 2; ++k) \
;         acc[ai][bj][m][n] = __builtin_amdgcn_mfma_f32_16x16x32_bf16(Bt[n][k], At[m][k], acc[ai][bj][m][n], 0, 0, 0); __builtin_amdgcn_s_setprio(0); } while (0)
; #define PG8_WAIT_V(n) asm volatile("s_waitcnt vmcnt(" #n ")" ::: "memory")
; #define PG8_WAIT_L(n) asm volatile("s_waitcnt lgkmcnt(" #n ")" ::: "memory")
; #define PG8_BAR __builtin_amdgcn_s_barrier()
; #define PG8_SCHED __builtin_amdgcn_sched_barrier(0)
; template <class Epi, class Sched, bool ALIGN_EPI = false, bool SP2 = false>
; __device__ __forceinline__ void gemm_phase(PG8_LAS unsigned char* lds, const Gemm g, const Sched& S, const Epi& E, int wid0) {
;     ...
;             PG8_WAIT_V(8); PG8_WAIT_L(0); PG8_BAR; PG8_MMA(1, 0, At, B0); PG8_MMA(1, 1, At, B1); PG8_BAR; PG8_SCHED;
;             PG8_LDB(B0, 1, 0); PG8_LDB(B1, 1, 1); PG8_SCHED; PG8_LDA(At, 1, 0); PG8_STAGE(PG8_SA(0, 1), a2 + hstepA, voffA);
;             PG8_WAIT_V(8); PG8_WAIT_L(0); PG8_BAR; PG8_MMA(0, 0, At, B0); PG8_MMA(0, 1, At, B1); PG8_BAR; PG8_SCHED;
	s_setprio 1
	s_waitcnt lgkmcnt(0)
	v_mfma_f32_16x16x32_bf16 v[62:65], v[138:141], v[172:175], 0
	v_mfma_f32_16x16x32_bf16 v[58:61], v[148:151], v[172:175], 0
	v_mfma_f32_16x16x32_bf16 v[46:49], v[138:141], v[180:183], 0
	v_mfma_f32_16x16x32_bf16 v[42:45], v[148:151], v[180:183], 0
	v_mfma_f32_16x16x32_bf16 v[30:33], v[138:141], v[188:191], 0
	v_mfma_f32_16x16x32_bf16 v[26:29], v[148:151], v[188:191], 0
	v_mfma_f32_16x16x32_bf16 v[14:17], v[138:141], v[196:199], 0
	v_mfma_f32_16x16x32_bf16 v[10:13], v[148:151], v[196:199], 0
	v_mfma_f32_16x16x32_bf16 v[62:65], v[144:147], v[176:179], v[62:65]
	v_mfma_f32_16x16x32_bf16 v[58:61], v[152:155], v[176:179], v[58:61]
	v_mfma_f32_16x16x32_bf16 v[46:49], v[144:147], v[184:187], v[46:49]
	v_mfma_f32_16x16x32_bf16 v[42:45], v[152:155], v[184:187], v[42:45]
	v_mfma_f32_16x16x32_bf16 v[30:33], v[144:147], v[192:195], v[30:33]
	v_mfma_f32_16x16x32_bf16 v[26:29], v[152:155], v[192:195], v[26:29]
	v_mfma_f32_16x16x32_bf16 v[14:17], v[144:147], v[200:203], v[14:17]
	v_mfma_f32_16x16x32_bf16 v[10:13], v[152:155], v[200:203], v[10:13]
	s_setprio 0
	s_setprio 1
	v_mfma_f32_16x16x32_bf16 v[54:57], v[156:159], v[172:175], 0
	v_mfma_f32_16x16x32_bf16 v[50:53], v[164:167], v[172:175], 0
	v_mfma_f32_16x16x32_bf16 v[38:41], v[156:159], v[180:183], 0
	v_mfma_f32_16x16x32_bf16 v[34:37], v[164:167], v[180:183], 0
	v_mfma_f32_16x16x32_bf16 v[22:25], v[156:159], v[188:191], 0
	v_mfma_f32_16x16x32_bf16 v[18:21], v[164:167], v[188:191], 0
	v_mfma_f32_16x16x32_bf16 v[6:9], v[156:159], v[196:199], 0
	v_mfma_f32_16x16x32_bf16 v[2:5], v[164:167], v[196:199], 0
	v_mfma_f32_16x16x32_bf16 v[54:57], v[160:163], v[176:179], v[54:57]
	v_mfma_f32_16x16x32_bf16 v[50:53], v[168:171], v[176:179], v[50:53]
	v_mfma_f32_16x16x32_bf16 v[38:41], v[160:163], v[184:187], v[38:41]
	v_mfma_f32_16x16x32_bf16 v[34:37], v[168:171], v[184:187], v[34:37]
	v_mfma_f32_16x16x32_bf16 v[22:25], v[160:163], v[192:195], v[22:25]
	v_mfma_f32_16x16x32_bf16 v[18:21], v[168:171], v[192:195], v[18:21]
	v_mfma_f32_16x16x32_bf16 v[6:9], v[160:163], v[200:203], v[6:9]
	v_mfma_f32_16x16x32_bf16 v[2:5], v[168:171], v[200:203], v[2:5]
	s_setprio 0
	s_barrier
	s_add_i32 s22, 0, 0x18000
	v_add_u32_e32 v142, s22, v1
	s_add_i32 s63, 0, 0x1c000
	ds_read_b128 v[138:141], v142
	ds_read_b128 v[144:147], v142 offset:1024
	ds_read_b128 v[148:151], v142 offset:2048
	ds_read_b128 v[152:155], v142 offset:3072
	v_add_u32_e32 v142, s63, v1
	ds_read_b128 v[156:159], v142
	ds_read_b128 v[160:163], v142 offset:1024
	ds_read_b128 v[164:167], v142 offset:2048
	ds_read_b128 v[168:171], v142 offset:3072
	s_add_u32 s14, s14, s60
	s_addc_u32 s15, s15, 0
	s_mov_b32 m0, s21
	v_lshl_add_u64 v[216:217], s[14:15], 0, v[132:133]
	ds_read_b128 v[172:175], v143 offset:32768
	ds_read_b128 v[176:179], v143 offset:33792
	ds_read_b128 v[180:183], v143 offset:34816
	ds_read_b128 v[184:187], v143 offset:35840
	ds_read_b128 v[188:191], v143 offset:36864
	ds_read_b128 v[192:195], v143 offset:37888
	ds_read_b128 v[196:199], v143 offset:38912
	ds_read_b128 v[200:203], v143 offset:39936
	global_load_lds_dwordx4 v[216:217], off
	v_lshl_add_u64 v[216:217], v[216:217], 0, s[36:37]
	s_mov_b32 m0, s23
	s_nop 0
	global_load_lds_dwordx4 v[216:217], off
	s_waitcnt vmcnt(8)
	s_waitcnt lgkmcnt(0)
	s_barrier
	s_setprio 1
	s_waitcnt lgkmcnt(0)
	v_mfma_f32_16x16x32_bf16 v[126:129], v[138:141], v[172:175], v[126:129]
	v_mfma_f32_16x16x32_bf16 v[122:125], v[148:151], v[172:175], v[122:125]
	v_mfma_f32_16x16x32_bf16 v[110:113], v[138:141], v[180:183], v[110:113]
	v_mfma_f32_16x16x32_bf16 v[106:109], v[148:151], v[180:183], v[106:109]
	v_mfma_f32_16x16x32_bf16 v[94:97], v[138:141], v[188:191], v[94:97]
	v_mfma_f32_16x16x32_bf16 v[90:93], v[148:151], v[188:191], v[90:93]
	v_mfma_f32_16x16x32_bf16 v[78:81], v[138:141], v[196:199], v[78:81]
	v_mfma_f32_16x16x32_bf16 v[74:77], v[148:151], v[196:199], v[74:77]
	v_mfma_f32_16x16x32_bf16 v[126:129], v[144:147], v[176:179], v[126:129]
	v_mfma_f32_16x16x32_bf16 v[122:125], v[152:155], v[176:179], v[122:125]
	v_mfma_f32_16x16x32_bf16 v[110:113], v[144:147], v[184:187], v[110:113]
	v_mfma_f32_16x16x32_bf16 v[106:109], v[152:155], v[184:187], v[106:109]
	v_mfma_f32_16x16x32_bf16 v[94:97], v[144:147], v[192:195], v[94:97]
	v_mfma_f32_16x16x32_bf16 v[90:93], v[152:155], v[192:195], v[90:93]
	v_mfma_f32_16x16x32_bf16 v[78:81], v[144:147], v[200:203], v[78:81]
	v_mfma_f32_16x16x32_bf16 v[74:77], v[152:155], v[200:203], v[74:77]
	s_setprio 0
	s_setprio 1
	v_mfma_f32_16x16x32_bf16 v[118:121], v[156:159], v[172:175], v[118:121]
	v_mfma_f32_16x16x32_bf16 v[114:117], v[164:167], v[172:175], v[114:117]
	v_mfma_f32_16x16x32_bf16 v[102:105], v[156:159], v[180:183], v[102:105]
	v_mfma_f32_16x16x32_bf16 v[98:101], v[164:167], v[180:183], v[98:101]
	v_mfma_f32_16x16x32_bf16 v[86:89], v[156:159], v[188:191], v[86:89]
	v_mfma_f32_16x16x32_bf16 v[82:85], v[164:167], v[188:191], v[82:85]
	v_mfma_f32_16x16x32_bf16 v[70:73], v[156:159], v[196:199], v[70:73]
	v_mfma_f32_16x16x32_bf16 v[66:69], v[164:167], v[196:199], v[66:69]
	v_mfma_f32_16x16x32_bf16 v[118:121], v[160:163], v[176:179], v[118:121]
	v_mfma_f32_16x16x32_bf16 v[114:117], v[168:171], v[176:179], v[114:117]
	v_mfma_f32_16x16x32_bf16 v[102:105], v[160:163], v[184:187], v[102:105]
	v_mfma_f32_16x16x32_bf16 v[98:101], v[168:171], v[184:187], v[98:101]
	v_mfma_f32_16x16x32_bf16 v[86:89], v[160:163], v[192:195], v[86:89]
	v_mfma_f32_16x16x32_bf16 v[82:85], v[168:171], v[192:195], v[82:85]
	v_mfma_f32_16x16x32_bf16 v[70:73], v[160:163], v[200:203], v[70:73]
	v_mfma_f32_16x16x32_bf16 v[66:69], v[168:171], v[200:203], v[66:69]
	s_setprio 0
	s_barrier
; #define PG8_STAGE(bufoff, gbase, voff) do { _Pragma("unroll") for (int _i = 0; _i < 2; ++_i) \
;         __builtin_amdgcn_global_load_lds((const unsigned*)((const char*)(gbase) + (size_t)_i * r64##voff + voff), (PG8_LAS unsigned*)(lds + (bufoff) + ldsw + _i * 8192), 16, 0, 0); } while (0)
; #define PG8_LDA(dst, b, h) do { _Pragma("unroll") for (int m = 0; m < 4; ++m) _Pragma("unroll") for (int k = 0; k < 2; ++k) dst[m][k] = *(const PG8_LAS bf16x8*)(lds + PG8_SA(b, h) + aoff + m * 2048 + k * 1024); } while (0)
; #define PG8_MMA(ai, bj, At, Bt) do { __builtin_amdgcn_s_setprio(1); _Pragma("unroll") for (int m = 0; m < 4; ++m) _Pragma("unroll") for (int n = 0; n < 2; ++n) _Pragma("unroll") for (int k = 0; k < 2; ++k) \
;         acc[ai][bj][m][n] = __builtin_amdgcn_mfma_f32_16x16x32_bf16(Bt[n][k], At[m][k], acc[ai][bj][m][n], 0, 0, 0); __builtin_amdgcn_s_setprio(0); } while (0)
; #define PG8_WAIT_V(n) asm volatile("s_waitcnt vmcnt(" #n ")" ::: "memory")
; #define PG8_WAIT_L(n) asm volatile("s_waitcnt lgkmcnt(" #n ")" ::: "memory")
; #define PG8_BAR __builtin_amdgcn_s_barrier()
; #define PG8_SCHED __builtin_amdgcn_sched_barrier(0)
; template <class Epi, class Sched, bool ALIGN_EPI = false, bool SP2 = false>
; __device__ __forceinline__ void gemm_phase(PG8_LAS unsigned char* lds, const Gemm g, const Sched& S, const Epi& E, int wid0) {
;     ...
;             PG8_LDA(At, 1, 1); PG8_STAGE(PG8_SB(1, 0), b3, voffB); PG8_STAGE(PG8_SB(1, 1), b3 + hstepB, voffB); PG8_STAGE(PG8_SA(1, 0), a3, voffA);
;             PG8_WAIT_V(8); PG8_WAIT_L(0); PG8_BAR; PG8_MMA(1, 0, At, B0); PG8_MMA(1, 1, At, B1); PG8_BAR; PG8_SCHED;
	s_add_i32 s14, s22, s17
	v_lshl_add_u64 v[204:205], v[204:205], 0, s[70:71]
	s_mov_b32 m0, s14
	ds_read_b128 v[172:175], v143 offset:49152
	ds_read_b128 v[176:179], v143 offset:50176
	ds_read_b128 v[180:183], v143 offset:51200
	ds_read_b128 v[184:187], v143 offset:52224
	ds_read_b128 v[188:191], v143 offset:53248
	ds_read_b128 v[192:195], v143 offset:54272
	ds_read_b128 v[196:199], v143 offset:55296
	ds_read_b128 v[200:203], v143 offset:56320
	global_load_lds_dwordx4 v[204:205], off
	v_lshl_add_u64 v[204:205], v[206:207], 0, s[70:71]
	s_add_i32 m0, s14, 0x2000
	s_add_i32 s14, s63, s17
	global_load_lds_dwordx4 v[204:205], off
	v_lshl_add_u64 v[204:205], v[208:209], 0, s[70:71]
	s_mov_b32 m0, s14
	s_nop 0
	global_load_lds_dwordx4 v[204:205], off
	v_lshl_add_u64 v[204:205], v[210:211], 0, s[70:71]
	s_add_i32 m0, s14, 0x2000
	s_nop 0
	global_load_lds_dwordx4 v[204:205], off
	v_lshl_add_u64 v[204:205], v[212:213], 0, s[70:71]
	s_mov_b32 m0, s56
	s_nop 0
	global_load_lds_dwordx4 v[204:205], off
	v_lshl_add_u64 v[204:205], v[214:215], 0, s[70:71]
	s_mov_b32 m0, s57
	s_nop 0
	global_load_lds_dwordx4 v[204:205], off
	s_waitcnt vmcnt(8)
	s_waitcnt lgkmcnt(0)
	s_barrier
	s_setprio 1
	s_waitcnt lgkmcnt(0)
	v_mfma_f32_16x16x32_bf16 v[62:65], v[138:141], v[172:175], v[62:65]
	v_mfma_f32_16x16x32_bf16 v[58:61], v[148:151], v[172:175], v[58:61]
	v_mfma_f32_16x16x32_bf16 v[46:49], v[138:141], v[180:183], v[46:49]
	v_mfma_f32_16x16x32_bf16 v[42:45], v[148:151], v[180:183], v[42:45]
	v_mfma_f32_16x16x32_bf16 v[30:33], v[138:141], v[188:191], v[30:33]
	v_mfma_f32_16x16x32_bf16 v[26:29], v[148:151], v[188:191], v[26:29]
	v_mfma_f32_16x16x32_bf16 v[14:17], v[138:141], v[196:199], v[14:17]
	v_mfma_f32_16x16x32_bf16 v[10:13], v[148:151], v[196:199], v[10:13]
	v_mfma_f32_16x16x32_bf16 v[62:65], v[144:147], v[176:179], v[62:65]
	v_mfma_f32_16x16x32_bf16 v[58:61], v[152:155], v[176:179], v[58:61]
	v_mfma_f32_16x16x32_bf16 v[46:49], v[144:147], v[184:187], v[46:49]
	v_mfma_f32_16x16x32_bf16 v[42:45], v[152:155], v[184:187], v[42:45]
	v_mfma_f32_16x16x32_bf16 v[30:33], v[144:147], v[192:195], v[30:33]
	v_mfma_f32_16x16x32_bf16 v[26:29], v[152:155], v[192:195], v[26:29]
	v_mfma_f32_16x16x32_bf16 v[14:17], v[144:147], v[200:203], v[14:17]
	v_mfma_f32_16x16x32_bf16 v[10:13], v[152:155], v[200:203], v[10:13]
	s_setprio 0
	s_setprio 1
	v_mfma_f32_16x16x32_bf16 v[54:57], v[156:159], v[172:175], v[54:57]
	v_mfma_f32_16x16x32_bf16 v[50:53], v[164:167], v[172:175], v[50:53]
	v_mfma_f32_16x16x32_bf16 v[38:41], v[156:159], v[180:183], v[38:41]
	v_mfma_f32_16x16x32_bf16 v[34:37], v[164:167], v[180:183], v[34:37]
	v_mfma_f32_16x16x32_bf16 v[22:25], v[156:159], v[188:191], v[22:25]
	v_mfma_f32_16x16x32_bf16 v[18:21], v[164:167], v[188:191], v[18:21]
	v_mfma_f32_16x16x32_bf16 v[6:9], v[156:159], v[196:199], v[6:9]
	v_mfma_f32_16x16x32_bf16 v[2:5], v[164:167], v[196:199], v[2:5]
	v_mfma_f32_16x16x32_bf16 v[54:57], v[160:163], v[176:179], v[54:57]
	v_mfma_f32_16x16x32_bf16 v[50:53], v[168:171], v[176:179], v[50:53]
	v_mfma_f32_16x16x32_bf16 v[38:41], v[160:163], v[184:187], v[38:41]
	v_mfma_f32_16x16x32_bf16 v[34:37], v[168:171], v[184:187], v[34:37]
	v_mfma_f32_16x16x32_bf16 v[22:25], v[160:163], v[192:195], v[22:25]
	v_mfma_f32_16x16x32_bf16 v[18:21], v[168:171], v[192:195], v[18:21]
	v_mfma_f32_16x16x32_bf16 v[6:9], v[160:163], v[200:203], v[6:9]
	v_mfma_f32_16x16x32_bf16 v[2:5], v[168:171], v[200:203], v[2:5]
	s_setprio 0
	s_barrier
	s_add_u32 s4, s4, 0x100
	s_addc_u32 s5, s5, 0
	s_add_u32 s90, s90, 0x100
	s_addc_u32 s91, s91, 0
	s_cmp_ge_u32 s92, s40
	s_mov_b32 s14, s92
	s_cbranch_scc1 .Lpeel_x_n1024

; #define PG8_BAR __builtin_amdgcn_s_barrier()
; template <class Epi, class Sched, bool ALIGN_EPI = false, bool SP2 = false>
; __device__ __forceinline__ void gemm_phase(PG8_LAS unsigned char* lds, const Gemm g, const Sched& S, const Epi& E, int wid0) {
;     ...
;         if constexpr (ALIGN_EPI) { if (wr == 0) PG8_BAR; }
.Lpeel_x_n1024:
	s_and_b64 vcc, exec, s[44:45]
	s_cbranch_vccz .LBB0_701
	s_barrier

; #define PG8_STAGE(bufoff, gbase, voff) do { _Pragma("unroll") for (int _i = 0; _i < 2; ++_i) \
;         __builtin_amdgcn_global_load_lds((const unsigned*)((const char*)(gbase) + (size_t)_i * r64##voff + voff), (PG8_LAS unsigned*)(lds + (bufoff) + ldsw + _i * 8192), 16, 0, 0); } while (0)
; #define PG8_LDA(dst, b, h) do { _Pragma("unroll") for (int m = 0; m < 4; ++m) _Pragma("unroll") for (int k = 0; k < 2; ++k) dst[m][k] = *(const PG8_LAS bf16x8*)(lds + PG8_SA(b, h) + aoff + m * 2048 + k * 1024); } while (0)
; #define PG8_LDB(dst, b, h) do { _Pragma("unroll") for (int n = 0; n < 2; ++n) _Pragma("unroll") for (int k = 0; k < 2; ++k) dst[n][k] = *(const PG8_LAS bf16x8*)(lds + PG8_SB(b, h) + boff + n * 2048 + k * 1024); } while (0)
; #define PG8_WAIT_V(n) asm volatile("s_waitcnt vmcnt(" #n ")" ::: "memory")
; #define PG8_WAIT_L(n) asm volatile("s_waitcnt lgkmcnt(" #n ")" ::: "memory")
; #define PG8_BAR __builtin_amdgcn_s_barrier()
; #define PG8_SCHED __builtin_amdgcn_sched_barrier(0)
; template <class Epi, class Sched, bool ALIGN_EPI = false, bool SP2 = false>
; __device__ __forceinline__ void gemm_phase(PG8_LAS unsigned char* lds, const Gemm g, const Sched& S, const Epi& E, int wid0) {
;     ...
;         PG8_STAGE(PG8_SB(1, 0), cB + kstep, voffB); PG8_STAGE(PG8_SA(1, 0), cA + kstep, voffA); PG8_STAGE(PG8_SB(1, 1), cB + hstepB + kstep, voffB);
;         PG8_WAIT_V(6); PG8_BAR;
;     ...
;             const bool last = (t == nt - 2);
;             const char* a1 = cA + (size_t)(t + 1) * kstep;
;             const char* a2 = last ? nA : cA + (size_t)(t + 2) * kstep; const char* b2 = last ? nB : cB + (size_t)(t + 2) * kstep;
;             const char* a3 = a2 + kstep; const char* b3 = b2 + kstep;
;             if (last && has_next) S.a_ready(nxt);
;             if constexpr (SP2) {
;             PG8_LDB(B0, 0, 0); PG8_LDB(B1, 0, 1); PG8_SCHED; PG8_LDA(At, 0, 0); PG8_STAGE(PG8_SA(1, 1), a1 + hstepA, voffA);
;             PG8_WAIT_V(8); PG8_WAIT_L(0); PG8_BAR; PG8_MMA(0, 0, At, B0); PG8_MMA(0, 1, At, B1); PG8_BAR; PG8_SCHED;
;             PG8_LDA(At, 0, 1); PG8_STAGE(PG8_SB(0, 0), b2, voffB); PG8_STAGE(PG8_SB(0, 1), b2 + hstepB, voffB); PG8_STAGE(PG8_SA(0, 0), a2, voffA);
;             PG8_WAIT_V(8); PG8_WAIT_L(0); PG8_BAR; PG8_MMA(1, 0, At, B0); PG8_MMA(1, 1, At, B1); PG8_BAR; PG8_SCHED;
.LBB0_828:
	v_lshl_add_u64 v[6:7], v[6:7], 0, s[70:71]
	s_add_i32 m0, s0, 0x18000
	s_and_b32 s1, s21, 3
	s_waitcnt vmcnt(2)
	s_barrier
	global_load_lds_dwordx4 v[6:7], off
	v_lshl_add_u64 v[6:7], v[8:9], 0, s[70:71]
	s_add_i32 m0, s0, 0x1a000
	s_add_i32 s21, s0, 0x8000
	global_load_lds_dwordx4 v[6:7], off
	v_lshl_add_u64 v[6:7], v[12:13], 0, s[70:71]
	s_mov_b32 m0, s21
	s_add_i32 s23, s0, 0xa000
	global_load_lds_dwordx4 v[6:7], off
	v_lshl_add_u64 v[6:7], v[10:11], 0, s[70:71]
	s_mov_b32 m0, s23
	v_lshl_add_u64 v[2:3], v[2:3], 0, s[70:71]
	global_load_lds_dwordx4 v[6:7], off
	s_add_i32 m0, s0, 0x1c000
	s_lshr_b32 s16, s14, 6
	global_load_lds_dwordx4 v[2:3], off
	v_lshl_add_u64 v[2:3], v[4:5], 0, s[70:71]
	s_add_i32 m0, s0, 0x1e000
	s_lshl_b32 s12, s15, 6
	global_load_lds_dwordx4 v[2:3], off
	v_and_b32_e32 v14, 48, v1
	s_lshl_b32 s14, s15, 13
	v_lshlrev_b32_e32 v15, 6, v1
	s_movk_i32 s15, 0x3c0
	v_lshlrev_b32_e32 v1, 2, v1
	v_and_or_b32 v14, v15, s15, v14
	v_and_b32_e32 v1, 32, v1
	s_waitcnt vmcnt(6)
	v_bitop3_b32 v15, v14, s14, v1 bitop3:0xde
	s_lshl_b32 s14, s1, 12
	v_bitop3_b32 v1, v14, s14, v1 bitop3:0xde
	s_add_i32 s40, s16, -2
	s_mov_b32 s14, 0
	v_add_u32_e32 v136, 0, v15
	s_barrier
.Lpeel_tail:
	s_add_i32 s44, s14, 2
	s_mov_b32 s45, s87
	s_or_b32 s86, s14, 1
	s_lshl_b64 s[46:47], s[44:45], 7
	s_cmp_lg_u32 s14, s40
	s_cselect_b32 s41, s46, 0
	s_cselect_b32 s22, s47, 0
	s_add_u32 s14, s10, s41
	s_addc_u32 s15, s11, s22
	s_add_i32 s43, 0, 0x10000
	s_add_u32 s46, s8, s41
	v_add_u32_e32 v137, s43, v1
	s_addc_u32 s47, s9, s22
	s_add_i32 s22, 0, 0x14000
	ds_read_b128 v[138:141], v137
	ds_read_b128 v[142:145], v137 offset:1024
	ds_read_b128 v[146:149], v137 offset:2048
	ds_read_b128 v[150:153], v137 offset:3072
	v_add_u32_e32 v137, s22, v1
	ds_read_b128 v[154:157], v137
	ds_read_b128 v[158:161], v137 offset:1024
	ds_read_b128 v[162:165], v137 offset:2048
	ds_read_b128 v[166:169], v137 offset:3072
	s_lshl_b64 s[56:57], s[86:87], 7
	v_lshl_add_u64 v[202:203], v[134:135], 0, s[56:57]
	s_add_i32 m0, s0, 0xc000
	ds_read_b128 v[170:173], v136
	ds_read_b128 v[174:177], v136 offset:1024
	ds_read_b128 v[178:181], v136 offset:2048
	ds_read_b128 v[182:185], v136 offset:3072
	ds_read_b128 v[186:189], v136 offset:4096
	ds_read_b128 v[190:193], v136 offset:5120
	ds_read_b128 v[194:197], v136 offset:6144
	ds_read_b128 v[198:201], v136 offset:7168
	global_load_lds_dwordx4 v[202:203], off
	v_lshl_add_u64 v[202:203], v[202:203], 0, s[36:37]
	s_add_i32 m0, s0, 0xe000
	s_nop 0
	global_load_lds_dwordx4 v[202:203], off
	s_waitcnt vmcnt(8)
	s_waitcnt lgkmcnt(0)
	s_barrier
	s_setprio 1
	s_waitcnt lgkmcnt(0)
	v_mfma_f32_16x16x32_bf16 v[126:129], v[138:141], v[170:173], 0
	v_mfma_f32_16x16x32_bf16 v[122:125], v[146:149], v[170:173], 0
	v_mfma_f32_16x16x32_bf16 v[110:113], v[138:141], v[178:181], 0
	v_mfma_f32_16x16x32_bf16 v[106:109], v[146:149], v[178:181], 0
	v_mfma_f32_16x16x32_bf16 v[94:97], v[138:141], v[186:189], 0
	v_mfma_f32_16x16x32_bf16 v[90:93], v[146:149], v[186:189], 0
	v_mfma_f32_16x16x32_bf16 v[78:81], v[138:141], v[194:197], 0
	v_mfma_f32_16x16x32_bf16 v[74:77], v[146:149], v[194:197], 0
	v_mfma_f32_16x16x32_bf16 v[126:129], v[142:145], v[174:177], v[126:129]
	v_mfma_f32_16x16x32_bf16 v[122:125], v[150:153], v[174:177], v[122:125]
	v_mfma_f32_16x16x32_bf16 v[110:113], v[142:145], v[182:185], v[110:113]
	v_mfma_f32_16x16x32_bf16 v[106:109], v[150:153], v[182:185], v[106:109]
	v_mfma_f32_16x16x32_bf16 v[94:97], v[142:145], v[190:193], v[94:97]
	v_mfma_f32_16x16x32_bf16 v[90:93], v[150:153], v[190:193], v[90:93]
	v_mfma_f32_16x16x32_bf16 v[78:81], v[142:145], v[198:201], v[78:81]
	v_mfma_f32_16x16x32_bf16 v[74:77], v[150:153], v[198:201], v[74:77]
	s_setprio 0
	s_setprio 1
	v_mfma_f32_16x16x32_bf16 v[118:121], v[154:157], v[170:173], 0
	v_mfma_f32_16x16x32_bf16 v[114:117], v[162:165], v[170:173], 0
	v_mfma_f32_16x16x32_bf16 v[102:105], v[154:157], v[178:181], 0
	v_mfma_f32_16x16x32_bf16 v[98:101], v[162:165], v[178:181], 0
	v_mfma_f32_16x16x32_bf16 v[86:89], v[154:157], v[186:189], 0
	v_mfma_f32_16x16x32_bf16 v[82:85], v[162:165], v[186:189], 0
	v_mfma_f32_16x16x32_bf16 v[70:73], v[154:157], v[194:197], 0
	v_mfma_f32_16x16x32_bf16 v[66:69], v[162:165], v[194:197], 0
	v_mfma_f32_16x16x32_bf16 v[118:121], v[158:161], v[174:177], v[118:121]
	v_mfma_f32_16x16x32_bf16 v[114:117], v[166:169], v[174:177], v[114:117]
	v_mfma_f32_16x16x32_bf16 v[102:105], v[158:161], v[182:185], v[102:105]
	v_mfma_f32_16x16x32_bf16 v[98:101], v[166:169], v[182:185], v[98:101]
	v_mfma_f32_16x16x32_bf16 v[86:89], v[158:161], v[190:193], v[86:89]
	v_mfma_f32_16x16x32_bf16 v[82:85], v[166:169], v[190:193], v[82:85]
	v_mfma_f32_16x16x32_bf16 v[70:73], v[158:161], v[198:201], v[70:73]
	v_mfma_f32_16x16x32_bf16 v[66:69], v[166:169], v[198:201], v[66:69]
	s_setprio 0
	s_barrier
	s_add_i32 s41, s43, s20
	v_lshl_add_u64 v[202:203], s[46:47], 0, v[130:131]
	s_mov_b32 m0, s41
	ds_read_b128 v[170:173], v136 offset:16384
	ds_read_b128 v[174:177], v136 offset:17408
	ds_read_b128 v[178:181], v136 offset:18432
	ds_read_b128 v[182:185], v136 offset:19456
	ds_read_b128 v[186:189], v136 offset:20480
	ds_read_b128 v[190:193], v136 offset:21504
	ds_read_b128 v[194:197], v136 offset:22528
	ds_read_b128 v[198:201], v136 offset:23552
	global_load_lds_dwordx4 v[202:203], off
	s_add_i32 m0, s41, 0x2000
	s_add_u32 s46, s46, s49
	v_lshl_add_u64 v[204:205], v[202:203], 0, s[82:83]
	s_addc_u32 s47, s47, 0
	s_add_i32 s22, s22, s20
	global_load_lds_dwordx4 v[204:205], off
	v_lshl_add_u64 v[206:207], s[46:47], 0, v[130:131]
	s_mov_b32 m0, s22
	v_lshl_add_u64 v[208:209], v[206:207], 0, s[82:83]
	global_load_lds_dwordx4 v[206:207], off
	s_add_i32 m0, s22, 0x2000
	v_lshl_add_u64 v[210:211], s[14:15], 0, v[132:133]
	global_load_lds_dwordx4 v[208:209], off
	s_mov_b32 m0, s0
	v_lshl_add_u64 v[212:213], v[210:211], 0, s[36:37]
	global_load_lds_dwordx4 v[210:211], off
	s_mov_b32 m0, s6
	s_nop 0
	global_load_lds_dwordx4 v[212:213], off
	s_waitcnt vmcnt(8)
	s_waitcnt lgkmcnt(0)
	s_barrier
; #define PG8_STAGE(bufoff, gbase, voff) do { _Pragma("unroll") for (int _i = 0; _i < 2; ++_i) \
;         __builtin_amdgcn_global_load_lds((const unsigned*)((const char*)(gbase) + (size_t)_i * r64##voff + voff), (PG8_LAS unsigned*)(lds + (bufoff) + ldsw + _i * 8192), 16, 0, 0); } while (0)
; #define PG8_LDA(dst, b, h) do { _Pragma("unroll") for (int m = 0; m < 4; ++m) _Pragma("unroll") for (int k = 0; k < 2; ++k) dst[m][k] = *(const PG8_LAS bf16x8*)(lds + PG8_SA(b, h) + aoff + m * 2048 + k * 1024); } while (0)
; #define PG8_LDB(dst, b, h) do { _Pragma("unroll") for (int n = 0; n < 2; ++n) _Pragma("unroll") for (int k = 0; k < 2; ++k) dst[n][k] = *(const PG8_LAS bf16x8*)(lds + PG8_SB(b, h) + boff + n * 2048 + k * 1024); } while (0)
; #define PG8_MMA(ai, bj, At, Bt) do { __builtin_amdgcn_s_setprio(1); _Pragma("unroll") for (int m = 0; m < 4; ++m) _Pragma("unroll") for (int n = 0; n < 2; ++n) _Pragma("unroll") for (int k = 0; k < 2; ++k) \
;         acc[ai][bj][m][n] = __builtin_amdgcn_mfma_f32_16x16x32_bf16(Bt[n][k], At[m][k], acc[ai][bj][m][n], 0, 0, 0); __builtin_amdgcn_s_setprio(0); } while (0)
; #define PG8_WAIT_V(n) asm volatile("s_waitcnt vmcnt(" #n ")" ::: "memory")
; #define PG8_WAIT_L(n) asm volatile("s_waitcnt lgkmcnt(" #n ")" ::: "memory")
; #define PG8_BAR __builtin_amdgcn_s_barrier()
; #define PG8_SCHED __builtin_amdgcn_sched_barrier(0)
; template <class Epi, class Sched, bool ALIGN_EPI = false, bool SP2 = false>
; __device__ __forceinline__ void gemm_phase(PG8_LAS unsigned char* lds, const Gemm g, const Sched& S, const Epi& E, int wid0) {
;     ...
;             PG8_WAIT_V(8); PG8_WAIT_L(0); PG8_BAR; PG8_MMA(1, 0, At, B0); PG8_MMA(1, 1, At, B1); PG8_BAR; PG8_SCHED;
;             PG8_LDB(B0, 1, 0); PG8_LDB(B1, 1, 1); PG8_SCHED; PG8_LDA(At, 1, 0); PG8_STAGE(PG8_SA(0, 1), a2 + hstepA, voffA);
;             PG8_WAIT_V(8); PG8_WAIT_L(0); PG8_BAR; PG8_MMA(0, 0, At, B0); PG8_MMA(0, 1, At, B1); PG8_BAR; PG8_SCHED;
	s_setprio 1
	s_waitcnt lgkmcnt(0)
	v_mfma_f32_16x16x32_bf16 v[62:65], v[138:141], v[170:173], 0
	v_mfma_f32_16x16x32_bf16 v[58:61], v[146:149], v[170:173], 0
	v_mfma_f32_16x16x32_bf16 v[46:49], v[138:141], v[178:181], 0
	v_mfma_f32_16x16x32_bf16 v[42:45], v[146:149], v[178:181], 0
	v_mfma_f32_16x16x32_bf16 v[30:33], v[138:141], v[186:189], 0
	v_mfma_f32_16x16x32_bf16 v[26:29], v[146:149], v[186:189], 0
	v_mfma_f32_16x16x32_bf16 v[14:17], v[138:141], v[194:197], 0
	v_mfma_f32_16x16x32_bf16 v[10:13], v[146:149], v[194:197], 0
	v_mfma_f32_16x16x32_bf16 v[62:65], v[142:145], v[174:177], v[62:65]
	v_mfma_f32_16x16x32_bf16 v[58:61], v[150:153], v[174:177], v[58:61]
	v_mfma_f32_16x16x32_bf16 v[46:49], v[142:145], v[182:185], v[46:49]
	v_mfma_f32_16x16x32_bf16 v[42:45], v[150:153], v[182:185], v[42:45]
	v_mfma_f32_16x16x32_bf16 v[30:33], v[142:145], v[190:193], v[30:33]
	v_mfma_f32_16x16x32_bf16 v[26:29], v[150:153], v[190:193], v[26:29]
	v_mfma_f32_16x16x32_bf16 v[14:17], v[142:145], v[198:201], v[14:17]
	v_mfma_f32_16x16x32_bf16 v[10:13], v[150:153], v[198:201], v[10:13]
	s_setprio 0
	s_setprio 1
	v_mfma_f32_16x16x32_bf16 v[54:57], v[154:157], v[170:173], 0
	v_mfma_f32_16x16x32_bf16 v[50:53], v[162:165], v[170:173], 0
	v_mfma_f32_16x16x32_bf16 v[38:41], v[154:157], v[178:181], 0
	v_mfma_f32_16x16x32_bf16 v[34:37], v[162:165], v[178:181], 0
	v_mfma_f32_16x16x32_bf16 v[22:25], v[154:157], v[186:189], 0
	v_mfma_f32_16x16x32_bf16 v[18:21], v[162:165], v[186:189], 0
	v_mfma_f32_16x16x32_bf16 v[6:9], v[154:157], v[194:197], 0
	v_mfma_f32_16x16x32_bf16 v[2:5], v[162:165], v[194:197], 0
	v_mfma_f32_16x16x32_bf16 v[54:57], v[158:161], v[174:177], v[54:57]
	v_mfma_f32_16x16x32_bf16 v[50:53], v[166:169], v[174:177], v[50:53]
	v_mfma_f32_16x16x32_bf16 v[38:41], v[158:161], v[182:185], v[38:41]
	v_mfma_f32_16x16x32_bf16 v[34:37], v[166:169], v[182:185], v[34:37]
	v_mfma_f32_16x16x32_bf16 v[22:25], v[158:161], v[190:193], v[22:25]
	v_mfma_f32_16x16x32_bf16 v[18:21], v[166:169], v[190:193], v[18:21]
	v_mfma_f32_16x16x32_bf16 v[6:9], v[158:161], v[198:201], v[6:9]
	v_mfma_f32_16x16x32_bf16 v[2:5], v[166:169], v[198:201], v[2:5]
	s_setprio 0
	s_barrier
	s_add_i32 s22, 0, 0x18000
	v_add_u32_e32 v137, s22, v1
	s_add_i32 s41, 0, 0x1c000
	ds_read_b128 v[138:141], v137
	ds_read_b128 v[142:145], v137 offset:1024
	ds_read_b128 v[146:149], v137 offset:2048
	ds_read_b128 v[150:153], v137 offset:3072
	v_add_u32_e32 v137, s41, v1
	ds_read_b128 v[154:157], v137
	ds_read_b128 v[158:161], v137 offset:1024
	ds_read_b128 v[162:165], v137 offset:2048
	ds_read_b128 v[166:169], v137 offset:3072
	s_add_u32 s14, s14, s60
	s_addc_u32 s15, s15, 0
	s_mov_b32 m0, s7
	v_lshl_add_u64 v[214:215], s[14:15], 0, v[132:133]
	ds_read_b128 v[170:173], v136 offset:32768
	ds_read_b128 v[174:177], v136 offset:33792
	ds_read_b128 v[178:181], v136 offset:34816
	ds_read_b128 v[182:185], v136 offset:35840
	ds_read_b128 v[186:189], v136 offset:36864
	ds_read_b128 v[190:193], v136 offset:37888
	ds_read_b128 v[194:197], v136 offset:38912
	ds_read_b128 v[198:201], v136 offset:39936
	global_load_lds_dwordx4 v[214:215], off
	v_lshl_add_u64 v[214:215], v[214:215], 0, s[36:37]
	s_mov_b32 m0, s13
	s_nop 0
	global_load_lds_dwordx4 v[214:215], off
	s_waitcnt vmcnt(8)
	s_waitcnt lgkmcnt(0)
	s_barrier
	s_setprio 1
	s_waitcnt lgkmcnt(0)
	v_mfma_f32_16x16x32_bf16 v[126:129], v[138:141], v[170:173], v[126:129]
	v_mfma_f32_16x16x32_bf16 v[122:125], v[146:149], v[170:173], v[122:125]
	v_mfma_f32_16x16x32_bf16 v[110:113], v[138:141], v[178:181], v[110:113]
	v_mfma_f32_16x16x32_bf16 v[106:109], v[146:149], v[178:181], v[106:109]
	v_mfma_f32_16x16x32_bf16 v[94:97], v[138:141], v[186:189], v[94:97]
	v_mfma_f32_16x16x32_bf16 v[90:93], v[146:149], v[186:189], v[90:93]
	v_mfma_f32_16x16x32_bf16 v[78:81], v[138:141], v[194:197], v[78:81]
	v_mfma_f32_16x16x32_bf16 v[74:77], v[146:149], v[194:197], v[74:77]
	v_mfma_f32_16x16x32_bf16 v[126:129], v[142:145], v[174:177], v[126:129]
	v_mfma_f32_16x16x32_bf16 v[122:125], v[150:153], v[174:177], v[122:125]
	v_mfma_f32_16x16x32_bf16 v[110:113], v[142:145], v[182:185], v[110:113]
	v_mfma_f32_16x16x32_bf16 v[106:109], v[150:153], v[182:185], v[106:109]
	v_mfma_f32_16x16x32_bf16 v[94:97], v[142:145], v[190:193], v[94:97]
	v_mfma_f32_16x16x32_bf16 v[90:93], v[150:153], v[190:193], v[90:93]
	v_mfma_f32_16x16x32_bf16 v[78:81], v[142:145], v[198:201], v[78:81]
	v_mfma_f32_16x16x32_bf16 v[74:77], v[150:153], v[198:201], v[74:77]
	s_setprio 0
	s_setprio 1
	v_mfma_f32_16x16x32_bf16 v[118:121], v[154:157], v[170:173], v[118:121]
	v_mfma_f32_16x16x32_bf16 v[114:117], v[162:165], v[170:173], v[114:117]
	v_mfma_f32_16x16x32_bf16 v[102:105], v[154:157], v[178:181], v[102:105]
	v_mfma_f32_16x16x32_bf16 v[98:101], v[162:165], v[178:181], v[98:101]
	v_mfma_f32_16x16x32_bf16 v[86:89], v[154:157], v[186:189], v[86:89]
	v_mfma_f32_16x16x32_bf16 v[82:85], v[162:165], v[186:189], v[82:85]
	v_mfma_f32_16x16x32_bf16 v[70:73], v[154:157], v[194:197], v[70:73]
	v_mfma_f32_16x16x32_bf16 v[66:69], v[162:165], v[194:197], v[66:69]
	v_mfma_f32_16x16x32_bf16 v[118:121], v[158:161], v[174:177], v[118:121]
	v_mfma_f32_16x16x32_bf16 v[114:117], v[166:169], v[174:177], v[114:117]
	v_mfma_f32_16x16x32_bf16 v[102:105], v[158:161], v[182:185], v[102:105]
	v_mfma_f32_16x16x32_bf16 v[98:101], v[166:169], v[182:185], v[98:101]
	v_mfma_f32_16x16x32_bf16 v[86:89], v[158:161], v[190:193], v[86:89]
	v_mfma_f32_16x16x32_bf16 v[82:85], v[166:169], v[190:193], v[82:85]
	v_mfma_f32_16x16x32_bf16 v[70:73], v[158:161], v[198:201], v[70:73]
	v_mfma_f32_16x16x32_bf16 v[66:69], v[166:169], v[198:201], v[66:69]
	s_setprio 0
	s_barrier
; #define PG8_STAGE(bufoff, gbase, voff) do { _Pragma("unroll") for (int _i = 0; _i < 2; ++_i) \
;         __builtin_amdgcn_global_load_lds((const unsigned*)((const char*)(gbase) + (size_t)_i * r64##voff + voff), (PG8_LAS unsigned*)(lds + (bufoff) + ldsw + _i * 8192), 16, 0, 0); } while (0)
; #define PG8_LDA(dst, b, h) do { _Pragma("unroll") for (int m = 0; m < 4; ++m) _Pragma("unroll") for (int k = 0; k < 2; ++k) dst[m][k] = *(const PG8_LAS bf16x8*)(lds + PG8_SA(b, h) + aoff + m * 2048 + k * 1024); } while (0)
; #define PG8_MMA(ai, bj, At, Bt) do { __builtin_amdgcn_s_setprio(1); _Pragma("unroll") for (int m = 0; m < 4; ++m) _Pragma("unroll") for (int n = 0; n < 2; ++n) _Pragma("unroll") for (int k = 0; k < 2; ++k) \
;         acc[ai][bj][m][n] = __builtin_amdgcn_mfma_f32_16x16x32_bf16(Bt[n][k], At[m][k], acc[ai][bj][m][n], 0, 0, 0); __builtin_amdgcn_s_setprio(0); } while (0)
; #define PG8_WAIT_V(n) asm volatile("s_waitcnt vmcnt(" #n ")" ::: "memory")
; #define PG8_WAIT_L(n) asm volatile("s_waitcnt lgkmcnt(" #n ")" ::: "memory")
; #define PG8_BAR __builtin_amdgcn_s_barrier()
; #define PG8_SCHED __builtin_amdgcn_sched_barrier(0)
; template <class Epi, class Sched, bool ALIGN_EPI = false, bool SP2 = false>
; __device__ __forceinline__ void gemm_phase(PG8_LAS unsigned char* lds, const Gemm g, const Sched& S, const Epi& E, int wid0) {
;     ...
;             PG8_LDA(At, 1, 1); PG8_STAGE(PG8_SB(1, 0), b3, voffB); PG8_STAGE(PG8_SB(1, 1), b3 + hstepB, voffB); PG8_STAGE(PG8_SA(1, 0), a3, voffA);
;             PG8_WAIT_V(8); PG8_WAIT_L(0); PG8_BAR; PG8_MMA(1, 0, At, B0); PG8_MMA(1, 1, At, B1); PG8_BAR; PG8_SCHED;
	s_add_i32 s14, s22, s20
	v_lshl_add_u64 v[202:203], v[202:203], 0, s[70:71]
	s_mov_b32 m0, s14
	ds_read_b128 v[170:173], v136 offset:49152
	ds_read_b128 v[174:177], v136 offset:50176
	ds_read_b128 v[178:181], v136 offset:51200
	ds_read_b128 v[182:185], v136 offset:52224
	ds_read_b128 v[186:189], v136 offset:53248
	ds_read_b128 v[190:193], v136 offset:54272
	ds_read_b128 v[194:197], v136 offset:55296
	ds_read_b128 v[198:201], v136 offset:56320
	global_load_lds_dwordx4 v[202:203], off
	v_lshl_add_u64 v[202:203], v[204:205], 0, s[70:71]
	s_add_i32 m0, s14, 0x2000
	s_add_i32 s14, s41, s20
	global_load_lds_dwordx4 v[202:203], off
	v_lshl_add_u64 v[202:203], v[206:207], 0, s[70:71]
	s_mov_b32 m0, s14
	s_nop 0
	global_load_lds_dwordx4 v[202:203], off
	v_lshl_add_u64 v[202:203], v[208:209], 0, s[70:71]
	s_add_i32 m0, s14, 0x2000
	s_nop 0
	global_load_lds_dwordx4 v[202:203], off
	v_lshl_add_u64 v[202:203], v[210:211], 0, s[70:71]
	s_mov_b32 m0, s21
	s_nop 0
	global_load_lds_dwordx4 v[202:203], off
	v_lshl_add_u64 v[202:203], v[212:213], 0, s[70:71]
	s_mov_b32 m0, s23
	s_nop 0
	global_load_lds_dwordx4 v[202:203], off
	s_waitcnt vmcnt(8)
	s_waitcnt lgkmcnt(0)
	s_barrier
	s_setprio 1
	s_waitcnt lgkmcnt(0)
	v_mfma_f32_16x16x32_bf16 v[62:65], v[138:141], v[170:173], v[62:65]
	v_mfma_f32_16x16x32_bf16 v[58:61], v[146:149], v[170:173], v[58:61]
	v_mfma_f32_16x16x32_bf16 v[46:49], v[138:141], v[178:181], v[46:49]
	v_mfma_f32_16x16x32_bf16 v[42:45], v[146:149], v[178:181], v[42:45]
	v_mfma_f32_16x16x32_bf16 v[30:33], v[138:141], v[186:189], v[30:33]
	v_mfma_f32_16x16x32_bf16 v[26:29], v[146:149], v[186:189], v[26:29]
	v_mfma_f32_16x16x32_bf16 v[14:17], v[138:141], v[194:197], v[14:17]
	v_mfma_f32_16x16x32_bf16 v[10:13], v[146:149], v[194:197], v[10:13]
	v_mfma_f32_16x16x32_bf16 v[62:65], v[142:145], v[174:177], v[62:65]
	v_mfma_f32_16x16x32_bf16 v[58:61], v[150:153], v[174:177], v[58:61]
	v_mfma_f32_16x16x32_bf16 v[46:49], v[142:145], v[182:185], v[46:49]
	v_mfma_f32_16x16x32_bf16 v[42:45], v[150:153], v[182:185], v[42:45]
	v_mfma_f32_16x16x32_bf16 v[30:33], v[142:145], v[190:193], v[30:33]
	v_mfma_f32_16x16x32_bf16 v[26:29], v[150:153], v[190:193], v[26:29]
	v_mfma_f32_16x16x32_bf16 v[14:17], v[142:145], v[198:201], v[14:17]
	v_mfma_f32_16x16x32_bf16 v[10:13], v[150:153], v[198:201], v[10:13]
	s_setprio 0
	s_setprio 1
	v_mfma_f32_16x16x32_bf16 v[54:57], v[154:157], v[170:173], v[54:57]
	v_mfma_f32_16x16x32_bf16 v[50:53], v[162:165], v[170:173], v[50:53]
	v_mfma_f32_16x16x32_bf16 v[38:41], v[154:157], v[178:181], v[38:41]
	v_mfma_f32_16x16x32_bf16 v[34:37], v[162:165], v[178:181], v[34:37]
	v_mfma_f32_16x16x32_bf16 v[22:25], v[154:157], v[186:189], v[22:25]
	v_mfma_f32_16x16x32_bf16 v[18:21], v[162:165], v[186:189], v[18:21]
	v_mfma_f32_16x16x32_bf16 v[6:9], v[154:157], v[194:197], v[6:9]
	v_mfma_f32_16x16x32_bf16 v[2:5], v[162:165], v[194:197], v[2:5]
	v_mfma_f32_16x16x32_bf16 v[54:57], v[158:161], v[174:177], v[54:57]
	v_mfma_f32_16x16x32_bf16 v[50:53], v[166:169], v[174:177], v[50:53]
	v_mfma_f32_16x16x32_bf16 v[38:41], v[158:161], v[182:185], v[38:41]
	v_mfma_f32_16x16x32_bf16 v[34:37], v[166:169], v[182:185], v[34:37]
	v_mfma_f32_16x16x32_bf16 v[22:25], v[158:161], v[190:193], v[22:25]
	v_mfma_f32_16x16x32_bf16 v[18:21], v[166:169], v[190:193], v[18:21]
	v_mfma_f32_16x16x32_bf16 v[6:9], v[158:161], v[198:201], v[6:9]
	v_mfma_f32_16x16x32_bf16 v[2:5], v[166:169], v[198:201], v[2:5]
	s_setprio 0
	s_barrier
	s_cmp_ge_u32 s44, s16
	s_mov_b32 s14, s44
	s_cbranch_scc1 .Lpeel_x_tail

; #define PG8_BAR __builtin_amdgcn_s_barrier()
; template <class Epi, class Sched, bool ALIGN_EPI = false, bool SP2 = false>
; __device__ __forceinline__ void gemm_phase(PG8_LAS unsigned char* lds, const Gemm g, const Sched& S, const Epi& E, int wid0) {
;     ...
;         if constexpr (ALIGN_EPI) { if (wr == 0) PG8_BAR; }
.Lpeel_x_tail:
	s_cmpk_lt_u32 s19, 0x100
	s_cbranch_scc0 .LBB0_832
	s_barrier
